# PP GEMM epilogue: row scale of the constants slot (exactly 1.0f) set directly instead of loaded and converted
# baseline (speedup 1.0000x reference)
; __device__ __forceinline__ unsigned cvt_pk_bf16(float lo, float hi) { unsigned r; asm volatile("v_cvt_pk_bf16_f32 %0, %1, %2" : "=v"(r) : "v"(lo), "v"(hi)); return r; }
; __device__ __forceinline__ float gelu_tanh(float x) { const float u = 0.7978845608028654f * (x + 0.044715f * x * x * x); return x * fast_rcp(1.0f + fast_exp2(-2.0f * LOG2E * u)); }
; __device__ __forceinline__ void load_rstd(float (&rsv)[2][4], const ssq_t* ssq, int row0) {
;     ssq_t t[2][4];
; #pragma unroll
;     for (int ai = 0; ai < 2; ++ai)
; #pragma unroll
;         for (int m = 0; m < 4; ++m) t[ai][m] = ssq[row0 + ai * HALF + m * 16];
; #pragma unroll
;     for (int ai = 0; ai < 2; ++ai)
; #pragma unroll
;         for (int m = 0; m < 4; ++m) rsv[ai][m] = __builtin_amdgcn_rsqf((float)t[ai][m] * (SSQ_INV / 1024.0f) + 1e-6f);
; }
;     __device__ __forceinline__ void operator()(const f32x4 (&acc)[2][2][4][2], const Unit& u, int wr, int wc, int fr, int fq) const {
;     ...
;             for (int m = 0; m < 4; ++m) { const int row = row0 + ai * HALF + m * 16; bf16_t* rowp = O + (size_t)row * ldc + col0; const float rs = rsv[ai][m];
; #pragma unroll
;                 for (int bj = 0; bj < 2; ++bj) { f32x4 v0 = acc[ai][bj][m][0] * rs, v1 = acc[ai][bj][m][1] * rs;
;                     if (ACT == 1) {
; #pragma unroll
;                         for (int j = 0; j < 4; ++j) { v0[j] = gelu_tanh(v0[j]); v1[j] = gelu_tanh(v1[j]); } }
;                     u32x4 w; w.x = cvt_pk_bf16(v0[0], v0[1]); w.y = cvt_pk_bf16(v0[2], v0[3]); w.z = cvt_pk_bf16(v1[0], v1[1]); w.w = cvt_pk_bf16(v1[2], v1[3]);
;                     *(u32x4*)(rowp + bj * HALF) = w; } }
.LBB0_382:
	v_mov_b32_e32 v135, v170
	s_lshl_b32 s17, s28, 8
	v_readfirstlane_b32 s15, v135
	s_ashr_i32 s28, s15, 2
	s_andn2_b32 s28, s28, 63
	s_lshr_b32 s15, s15, 1
	s_add_i32 s28, s28, s17
	s_lshl_b32 s17, s29, 8
	s_and_b32 s15, s15, 0x60
	v_and_or_b32 v134, v135, 15, s28
	s_or_b32 s15, s15, s17
	v_lshrrev_b32_e32 v135, 1, v135
	v_readlane_b32 s28, v255, 49
	v_and_or_b32 v142, v135, 24, s15
	v_ashrrev_i32_e32 v135, 31, v134
	v_readlane_b32 s29, v255, 50
	s_mov_b32 s15, 0x48000
	s_nop 0
	v_lshl_add_u64 v[146:147], v[134:135], 3, s[28:29]
	s_mov_b64 s[28:29], 0x40000
	v_ffbh_u32_e32 v140, v149
	v_min_u32_e32 v140, 32, v140
	v_lshlrev_b64 v[146:147], v140, v[148:149]
	v_min_u32_e32 v143, 1, v146
	v_or_b32_e32 v143, v147, v143
	v_cvt_f32_u32_e32 v143, v143
	v_sub_u32_e32 v140, 32, v140
	v_ldexp_f32 v140, v143, v140
	v_fmamk_f32 v140, v140, 0x30800000, v223
	v_mov_b32_e32 v150, 1.0
	v_ffbh_u32_e32 v140, v155
	v_min_u32_e32 v140, 32, v140
	v_lshlrev_b64 v[146:147], v140, v[154:155]
	v_min_u32_e32 v143, 1, v146
	v_or_b32_e32 v143, v147, v143
	v_cvt_f32_u32_e32 v143, v143
	v_sub_u32_e32 v140, 32, v140
	v_pk_mul_f32 v[126:127], v[126:127], v[150:151] op_sel_hi:[1,0]
	v_pk_mul_f32 v[124:125], v[124:125], v[150:151] op_sel_hi:[1,0]
	v_ldexp_f32 v140, v143, v140
	v_fmamk_f32 v140, v140, 0x30800000, v223
	v_mov_b32_e32 v148, 1.0
	v_ffbh_u32_e32 v140, v157
	v_min_u32_e32 v140, 32, v140
	v_lshlrev_b64 v[146:147], v140, v[156:157]
	v_min_u32_e32 v143, 1, v146
	v_or_b32_e32 v143, v147, v143
	v_cvt_f32_u32_e32 v143, v143
	v_sub_u32_e32 v140, 32, v140
	v_pk_mul_f32 v[116:117], v[116:117], v[150:151] op_sel_hi:[1,0]
	v_pk_mul_f32 v[118:119], v[118:119], v[150:151] op_sel_hi:[1,0]
	v_ldexp_f32 v140, v143, v140
	v_fmamk_f32 v140, v140, 0x30800000, v223
	v_mov_b32_e32 v146, 1.0
	v_ffbh_u32_e32 v140, v159
	v_min_u32_e32 v140, 32, v140
	v_lshlrev_b64 v[154:155], v140, v[158:159]
	v_min_u32_e32 v143, 1, v154
	v_or_b32_e32 v143, v155, v143
	v_cvt_f32_u32_e32 v143, v143
	v_sub_u32_e32 v140, 32, v140
	v_pk_mul_f32 v[110:111], v[110:111], v[148:149] op_sel_hi:[1,0]
	v_pk_mul_f32 v[108:109], v[108:109], v[148:149] op_sel_hi:[1,0]
	v_ldexp_f32 v140, v143, v140
	v_fmamk_f32 v140, v140, 0x30800000, v223
	v_mov_b32_e32 v144, 1.0
	v_ffbh_u32_e32 v140, v161
	v_min_u32_e32 v140, 32, v140
	v_lshlrev_b64 v[154:155], v140, v[160:161]
	v_min_u32_e32 v143, 1, v154
	v_or_b32_e32 v143, v155, v143
	v_cvt_f32_u32_e32 v143, v143
	v_sub_u32_e32 v140, 32, v140
	v_lshlrev_b64 v[154:155], 11, v[134:135]
	v_lshl_add_u64 v[154:155], s[20:21], 0, v[154:155]
	v_ldexp_f32 v140, v143, v140
	v_ffbh_u32_e32 v143, v139
	v_min_u32_e32 v143, 32, v143
	v_lshlrev_b64 v[138:139], v143, v[138:139]
	v_min_u32_e32 v138, 1, v138
	v_or_b32_e32 v138, v139, v138
	v_sub_u32_e32 v139, 32, v143
	v_ashrrev_i32_e32 v143, 31, v142
	v_lshlrev_b64 v[156:157], 1, v[142:143]
	v_lshl_add_u64 v[142:143], v[154:155], 0, v[156:157]
	v_pk_mul_f32 v[154:155], v[122:123], v[150:151] op_sel_hi:[1,0]
	v_pk_mul_f32 v[122:123], v[120:121], v[150:151] op_sel_hi:[1,0]
	v_cvt_pk_bf16_f32 v120, v124, v125
	v_cvt_pk_bf16_f32 v121, v126, v127
	v_cvt_f32_u32_e32 v138, v138
	v_cvt_pk_bf16_f32 v122, v122, v123
	v_cvt_pk_bf16_f32 v123, v154, v155
	global_store_dwordx4 v[142:143], v[120:123], off
	v_ldexp_f32 v138, v138, v139
	v_ffbh_u32_e32 v139, v137
	v_pk_mul_f32 v[120:121], v[114:115], v[150:151] op_sel_hi:[1,0]
	v_pk_mul_f32 v[114:115], v[112:113], v[150:151] op_sel_hi:[1,0]
	v_cvt_pk_bf16_f32 v112, v116, v117
	v_cvt_pk_bf16_f32 v113, v118, v119
	v_pk_mul_f32 v[100:101], v[100:101], v[148:149] op_sel_hi:[1,0]
	v_cvt_pk_bf16_f32 v114, v114, v115
	v_cvt_pk_bf16_f32 v115, v120, v121
	global_store_dwordx4 v[142:143], v[112:115], off offset:256
	v_min_u32_e32 v139, 32, v139
	v_pk_mul_f32 v[102:103], v[102:103], v[148:149] op_sel_hi:[1,0]
	v_or_b32_e32 v112, 16, v134
	v_ashrrev_i32_e32 v113, 31, v112
	v_lshlrev_b64 v[112:113], 11, v[112:113]
	v_lshl_add_u64 v[112:113], s[20:21], 0, v[112:113]
	v_lshl_add_u64 v[112:113], v[112:113], 0, v[156:157]
	v_pk_mul_f32 v[114:115], v[106:107], v[148:149] op_sel_hi:[1,0]
	v_pk_mul_f32 v[106:107], v[104:105], v[148:149] op_sel_hi:[1,0]
	v_cvt_pk_bf16_f32 v104, v108, v109
	v_cvt_pk_bf16_f32 v105, v110, v111
	v_lshlrev_b64 v[136:137], v139, v[136:137]
	v_cvt_pk_bf16_f32 v106, v106, v107
	v_cvt_pk_bf16_f32 v107, v114, v115
	global_store_dwordx4 v[112:113], v[104:107], off
	v_min_u32_e32 v136, 1, v136
	v_or_b32_e32 v136, v137, v136
	v_pk_mul_f32 v[104:105], v[98:99], v[148:149] op_sel_hi:[1,0]
	v_pk_mul_f32 v[98:99], v[96:97], v[148:149] op_sel_hi:[1,0]
	v_cvt_pk_bf16_f32 v96, v100, v101
	v_cvt_pk_bf16_f32 v97, v102, v103
	v_cvt_f32_u32_e32 v136, v136
	v_cvt_pk_bf16_f32 v98, v98, v99
	v_cvt_pk_bf16_f32 v99, v104, v105
	global_store_dwordx4 v[112:113], v[96:99], off offset:256
	v_pk_mul_f32 v[94:95], v[94:95], v[146:147] op_sel_hi:[1,0]
	v_pk_mul_f32 v[92:93], v[92:93], v[146:147] op_sel_hi:[1,0]
	v_or_b32_e32 v96, 32, v134
	v_ashrrev_i32_e32 v97, 31, v96
	v_lshlrev_b64 v[96:97], 11, v[96:97]
	v_lshl_add_u64 v[96:97], s[20:21], 0, v[96:97]
	v_lshl_add_u64 v[96:97], v[96:97], 0, v[156:157]
	v_pk_mul_f32 v[98:99], v[90:91], v[146:147] op_sel_hi:[1,0]
	v_pk_mul_f32 v[90:91], v[88:89], v[146:147] op_sel_hi:[1,0]
	v_cvt_pk_bf16_f32 v88, v92, v93
	v_cvt_pk_bf16_f32 v89, v94, v95
	v_pk_mul_f32 v[84:85], v[84:85], v[146:147] op_sel_hi:[1,0]
	v_cvt_pk_bf16_f32 v90, v90, v91
	v_cvt_pk_bf16_f32 v91, v98, v99
	global_store_dwordx4 v[96:97], v[88:91], off
	v_pk_mul_f32 v[86:87], v[86:87], v[146:147] op_sel_hi:[1,0]
	v_fmamk_f32 v140, v140, 0x30800000, v223
	v_pk_mul_f32 v[88:89], v[82:83], v[146:147] op_sel_hi:[1,0]
; __device__ __forceinline__ unsigned cvt_pk_bf16(float lo, float hi) { unsigned r; asm volatile("v_cvt_pk_bf16_f32 %0, %1, %2" : "=v"(r) : "v"(lo), "v"(hi)); return r; }
; __device__ __forceinline__ float gelu_tanh(float x) { const float u = 0.7978845608028654f * (x + 0.044715f * x * x * x); return x * fast_rcp(1.0f + fast_exp2(-2.0f * LOG2E * u)); }
;     __device__ __forceinline__ void operator()(const f32x4 (&acc)[2][2][4][2], const Unit& u, int wr, int wc, int fr, int fq) const {
;     ...
;             for (int m = 0; m < 4; ++m) { const int row = row0 + ai * HALF + m * 16; bf16_t* rowp = O + (size_t)row * ldc + col0; const float rs = rsv[ai][m];
; #pragma unroll
;                 for (int bj = 0; bj < 2; ++bj) { f32x4 v0 = acc[ai][bj][m][0] * rs, v1 = acc[ai][bj][m][1] * rs;
;                     if (ACT == 1) {
; #pragma unroll
;                         for (int j = 0; j < 4; ++j) { v0[j] = gelu_tanh(v0[j]); v1[j] = gelu_tanh(v1[j]); } }
;                     u32x4 w; w.x = cvt_pk_bf16(v0[0], v0[1]); w.y = cvt_pk_bf16(v0[2], v0[3]); w.z = cvt_pk_bf16(v1[0], v1[1]); w.w = cvt_pk_bf16(v1[2], v1[3]);
;                     *(u32x4*)(rowp + bj * HALF) = w; } }
	v_pk_mul_f32 v[82:83], v[80:81], v[146:147] op_sel_hi:[1,0]
	v_cvt_pk_bf16_f32 v80, v84, v85
	v_cvt_pk_bf16_f32 v81, v86, v87
	v_sub_u32_e32 v137, 32, v139
	v_cvt_pk_bf16_f32 v82, v82, v83
	v_cvt_pk_bf16_f32 v83, v88, v89
	global_store_dwordx4 v[96:97], v[80:83], off offset:256
	v_mov_b32_e32 v140, 1.0
	v_ldexp_f32 v136, v136, v137
	v_or_b32_e32 v80, 48, v134
	v_ashrrev_i32_e32 v81, 31, v80
	v_ffbh_u32_e32 v137, v153
	v_lshlrev_b64 v[80:81], 11, v[80:81]
	v_min_u32_e32 v137, 32, v137
	v_lshl_add_u64 v[80:81], s[20:21], 0, v[80:81]
	v_lshlrev_b64 v[152:153], v137, v[152:153]
	v_lshl_add_u64 v[80:81], v[80:81], 0, v[156:157]
	v_pk_mul_f32 v[78:79], v[78:79], v[144:145] op_sel_hi:[1,0]
	v_pk_mul_f32 v[76:77], v[76:77], v[144:145] op_sel_hi:[1,0]
	v_pk_mul_f32 v[82:83], v[74:75], v[144:145] op_sel_hi:[1,0]
	v_pk_mul_f32 v[74:75], v[72:73], v[144:145] op_sel_hi:[1,0]
	v_cvt_pk_bf16_f32 v72, v76, v77
	v_cvt_pk_bf16_f32 v73, v78, v79
	v_min_u32_e32 v139, 1, v152
	v_cvt_pk_bf16_f32 v74, v74, v75
	v_cvt_pk_bf16_f32 v75, v82, v83
	global_store_dwordx4 v[80:81], v[72:75], off
	v_fmamk_f32 v138, v138, 0x30800000, v223
	v_or_b32_e32 v139, v153, v139
	v_pk_mul_f32 v[72:73], v[66:67], v[144:145] op_sel_hi:[1,0]
	v_pk_mul_f32 v[66:67], v[64:65], v[144:145] op_sel_hi:[1,0]
	v_pk_mul_f32 v[70:71], v[70:71], v[144:145] op_sel_hi:[1,0]
	v_pk_mul_f32 v[68:69], v[68:69], v[144:145] op_sel_hi:[1,0]
	v_pk_mul_f32 v[60:61], v[60:61], v[140:141] op_sel_hi:[1,0]
	v_cvt_pk_bf16_f32 v64, v68, v69
	v_cvt_pk_bf16_f32 v65, v70, v71
	v_cvt_pk_bf16_f32 v66, v66, v67
	v_cvt_pk_bf16_f32 v67, v72, v73
	v_mov_b32_e32 v138, 1.0
	v_cvt_f32_u32_e32 v139, v139
	global_store_dwordx4 v[80:81], v[64:67], off offset:256
	v_pk_mul_f32 v[62:63], v[62:63], v[140:141] op_sel_hi:[1,0]
	v_pk_mul_f32 v[54:55], v[54:55], v[140:141] op_sel_hi:[1,0]
	v_pk_mul_f32 v[66:67], v[58:59], v[140:141] op_sel_hi:[1,0]
	v_pk_mul_f32 v[58:59], v[56:57], v[140:141] op_sel_hi:[1,0]
	v_cvt_pk_bf16_f32 v56, v60, v61
	v_add_co_u32_e32 v60, vcc, s72, v142
	v_cvt_pk_bf16_f32 v57, v62, v63
	v_cvt_pk_bf16_f32 v58, v58, v59
	v_cvt_pk_bf16_f32 v59, v66, v67
	v_lshl_add_u64 v[64:65], v[142:143], 0, s[28:29]
	s_nop 0
	v_addc_co_u32_e32 v61, vcc, 0, v143, vcc
	global_store_dwordx4 v[60:61], v[56:59], off
	v_pk_mul_f32 v[52:53], v[52:53], v[140:141] op_sel_hi:[1,0]
	v_fmamk_f32 v136, v136, 0x30800000, v223
	v_pk_mul_f32 v[56:57], v[46:47], v[140:141] op_sel_hi:[1,0]
	v_pk_mul_f32 v[46:47], v[44:45], v[140:141] op_sel_hi:[1,0]
	v_cvt_pk_bf16_f32 v44, v52, v53
	v_cvt_pk_bf16_f32 v45, v54, v55
	v_mov_b32_e32 v136, 1.0
	v_cvt_pk_bf16_f32 v46, v46, v47
	v_cvt_pk_bf16_f32 v47, v56, v57
	global_store_dwordx4 v[64:65], v[44:47], off offset:256
	v_pk_mul_f32 v[48:49], v[48:49], v[138:139] op_sel_hi:[1,0]
	v_sub_u32_e32 v137, 32, v137
	v_pk_mul_f32 v[46:47], v[50:51], v[138:139] op_sel_hi:[1,0]
	v_pk_mul_f32 v[50:51], v[42:43], v[138:139] op_sel_hi:[1,0]
	v_pk_mul_f32 v[42:43], v[40:41], v[138:139] op_sel_hi:[1,0]
	v_cvt_pk_bf16_f32 v40, v48, v49
	v_cvt_pk_bf16_f32 v41, v46, v47
	v_add_co_u32_e32 v46, vcc, s15, v142
	v_ldexp_f32 v137, v139, v137
	s_nop 0
	v_addc_co_u32_e32 v47, vcc, 0, v143, vcc
	s_mov_b64 s[28:29], 0x48000
	v_cvt_pk_bf16_f32 v42, v42, v43
	v_cvt_pk_bf16_f32 v43, v50, v51
	global_store_dwordx4 v[46:47], v[40:43], off
	v_fmamk_f32 v137, v137, 0x30800000, v223
	v_lshl_add_u64 v[44:45], v[142:143], 0, s[28:29]
	v_pk_mul_f32 v[40:41], v[30:31], v[138:139] op_sel_hi:[1,0]
	v_pk_mul_f32 v[30:31], v[28:29], v[138:139] op_sel_hi:[1,0]
	v_pk_mul_f32 v[38:39], v[38:39], v[138:139] op_sel_hi:[1,0]
	v_pk_mul_f32 v[36:37], v[36:37], v[138:139] op_sel_hi:[1,0]
	v_mov_b32_e32 v152, 1.0
	v_cvt_pk_bf16_f32 v28, v36, v37
	v_cvt_pk_bf16_f32 v29, v38, v39
	v_cvt_pk_bf16_f32 v30, v30, v31
	v_cvt_pk_bf16_f32 v31, v40, v41
	global_store_dwordx4 v[44:45], v[28:31], off offset:256
	v_pk_mul_f32 v[32:33], v[32:33], v[136:137] op_sel_hi:[1,0]
	s_mov_b64 s[28:29], 0x50000
	v_pk_mul_f32 v[30:31], v[34:35], v[136:137] op_sel_hi:[1,0]
	v_pk_mul_f32 v[34:35], v[26:27], v[136:137] op_sel_hi:[1,0]
	v_pk_mul_f32 v[26:27], v[24:25], v[136:137] op_sel_hi:[1,0]
	v_cvt_pk_bf16_f32 v24, v32, v33
	v_cvt_pk_bf16_f32 v25, v30, v31
	v_add_co_u32_e32 v30, vcc, s77, v142
	v_cvt_pk_bf16_f32 v26, v26, v27
	v_cvt_pk_bf16_f32 v27, v34, v35
	v_lshl_add_u64 v[28:29], v[142:143], 0, s[28:29]
	s_nop 0
	v_addc_co_u32_e32 v31, vcc, 0, v143, vcc
	global_store_dwordx4 v[30:31], v[24:27], off
	v_pk_mul_f32 v[22:23], v[22:23], v[136:137] op_sel_hi:[1,0]
	v_pk_mul_f32 v[20:21], v[20:21], v[136:137] op_sel_hi:[1,0]
	v_pk_mul_f32 v[24:25], v[14:15], v[136:137] op_sel_hi:[1,0]
	v_pk_mul_f32 v[14:15], v[12:13], v[136:137] op_sel_hi:[1,0]
	v_cvt_pk_bf16_f32 v12, v20, v21
	v_cvt_pk_bf16_f32 v13, v22, v23
	s_mov_b32 s15, 0x58000
	v_cvt_pk_bf16_f32 v14, v14, v15
	v_cvt_pk_bf16_f32 v15, v24, v25
	global_store_dwordx4 v[28:29], v[12:15], off offset:256
	v_pk_mul_f32 v[16:17], v[16:17], v[152:153] op_sel_hi:[1,0]
	s_mov_b64 s[28:29], 0x58000
	v_pk_mul_f32 v[14:15], v[18:19], v[152:153] op_sel_hi:[1,0]
	v_pk_mul_f32 v[18:19], v[10:11], v[152:153] op_sel_hi:[1,0]
	v_pk_mul_f32 v[10:11], v[8:9], v[152:153] op_sel_hi:[1,0]
	v_cvt_pk_bf16_f32 v8, v16, v17
	v_cvt_pk_bf16_f32 v9, v14, v15
	v_add_co_u32_e32 v14, vcc, s15, v142
	v_lshl_add_u64 v[12:13], v[142:143], 0, s[28:29]
	s_nop 0
	v_addc_co_u32_e32 v15, vcc, 0, v143, vcc
	v_cvt_pk_bf16_f32 v10, v10, v11
	v_cvt_pk_bf16_f32 v11, v18, v19
	global_store_dwordx4 v[14:15], v[8:11], off
	s_mov_b64 s[28:29], -1
	s_andn2_b64 vcc, exec, s[8:9]
	v_pk_mul_f32 v[8:9], v[2:3], v[152:153] op_sel_hi:[1,0]
	v_pk_mul_f32 v[2:3], v[0:1], v[152:153] op_sel_hi:[1,0]
	v_pk_mul_f32 v[6:7], v[6:7], v[152:153] op_sel_hi:[1,0]
	v_pk_mul_f32 v[4:5], v[4:5], v[152:153] op_sel_hi:[1,0]
	s_nop 0
	v_cvt_pk_bf16_f32 v0, v4, v5
	v_cvt_pk_bf16_f32 v1, v6, v7
	v_cvt_pk_bf16_f32 v2, v2, v3
	v_cvt_pk_bf16_f32 v3, v8, v9
	global_store_dwordx4 v[12:13], v[0:3], off offset:256
	s_cbranch_vccnz .LBB0_371
	s_andn2_b64 vcc, exec, s[10:11]
	s_cbranch_vccnz .LBB0_370
	s_barrier
	s_branch .LBB0_370
